# SwiGLU GEMM epilogue hand-written: packed mul/add on pairs, batched exp/rcp without pads, 32-bit offset stores (about 310 instead of 600 instructions per tile per wave)
# speedup vs baseline: 1.0136x; 1.0136x over previous
.LBB0_226:
	s_andn2_b64 vcc, exec, s[0:1]
	s_cbranch_vccnz .LBB0_133
	v_lshl_or_b32 v130, s18, 7, v238
	v_mad_u32_u24 v130, v196, s75, v130
	v_mov_b32_e32 v146, 0xbfb8aa3b
	v_lshlrev_b32_e32 v130, 1, v130
	v_pk_mul_f32 v[142:143], v[124:125], v[146:147] op_sel_hi:[1,0]
	v_pk_mul_f32 v[144:145], v[126:127], v[146:147] op_sel_hi:[1,0]
	v_exp_f32_e32 v142, v142
	v_exp_f32_e32 v143, v143
	v_exp_f32_e32 v144, v144
	v_exp_f32_e32 v145, v145
	v_pk_add_f32 v[142:143], v[142:143], 1.0 op_sel_hi:[1,0]
	v_pk_add_f32 v[144:145], v[144:145], 1.0 op_sel_hi:[1,0]
	v_rcp_f32_e32 v142, v142
	v_rcp_f32_e32 v143, v143
	v_rcp_f32_e32 v144, v144
	v_rcp_f32_e32 v145, v145
	v_pk_mul_f32 v[124:125], v[124:125], v[142:143]
	v_pk_mul_f32 v[126:127], v[126:127], v[144:145]
	v_pk_mul_f32 v[124:125], v[124:125], v[120:121]
	v_pk_mul_f32 v[126:127], v[126:127], v[122:123]
	v_pk_mul_f32 v[142:143], v[116:117], v[146:147] op_sel_hi:[1,0]
	v_pk_mul_f32 v[144:145], v[118:119], v[146:147] op_sel_hi:[1,0]
	v_exp_f32_e32 v142, v142
	v_exp_f32_e32 v143, v143
	v_exp_f32_e32 v144, v144
	v_exp_f32_e32 v145, v145
	v_pk_add_f32 v[142:143], v[142:143], 1.0 op_sel_hi:[1,0]
	v_pk_add_f32 v[144:145], v[144:145], 1.0 op_sel_hi:[1,0]
	v_rcp_f32_e32 v142, v142
	v_rcp_f32_e32 v143, v143
	v_rcp_f32_e32 v144, v144
	v_rcp_f32_e32 v145, v145
	v_pk_mul_f32 v[116:117], v[116:117], v[142:143]
	v_pk_mul_f32 v[118:119], v[118:119], v[144:145]
	v_pk_mul_f32 v[116:117], v[116:117], v[112:113]
	v_pk_mul_f32 v[118:119], v[118:119], v[114:115]
	v_cvt_pk_bf16_f32 v112, v124, v125
	v_cvt_pk_bf16_f32 v113, v126, v127
	v_cvt_pk_bf16_f32 v114, v116, v117
	v_cvt_pk_bf16_f32 v115, v118, v119
	global_store_dwordx4 v130, v[112:115], s[86:87]
	v_add_u32_e32 v130, 0x16000, v130
	v_pk_mul_f32 v[142:143], v[108:109], v[146:147] op_sel_hi:[1,0]
	v_pk_mul_f32 v[144:145], v[110:111], v[146:147] op_sel_hi:[1,0]
	v_exp_f32_e32 v142, v142
	v_exp_f32_e32 v143, v143
	v_exp_f32_e32 v144, v144
	v_exp_f32_e32 v145, v145
	v_pk_add_f32 v[142:143], v[142:143], 1.0 op_sel_hi:[1,0]
	v_pk_add_f32 v[144:145], v[144:145], 1.0 op_sel_hi:[1,0]
	v_rcp_f32_e32 v142, v142
	v_rcp_f32_e32 v143, v143
	v_rcp_f32_e32 v144, v144
	v_rcp_f32_e32 v145, v145
	v_pk_mul_f32 v[108:109], v[108:109], v[142:143]
	v_pk_mul_f32 v[110:111], v[110:111], v[144:145]
	v_pk_mul_f32 v[108:109], v[108:109], v[104:105]
	v_pk_mul_f32 v[110:111], v[110:111], v[106:107]
	v_pk_mul_f32 v[142:143], v[100:101], v[146:147] op_sel_hi:[1,0]
	v_pk_mul_f32 v[144:145], v[102:103], v[146:147] op_sel_hi:[1,0]
	v_exp_f32_e32 v142, v142
	v_exp_f32_e32 v143, v143
	v_exp_f32_e32 v144, v144
	v_exp_f32_e32 v145, v145
	v_pk_add_f32 v[142:143], v[142:143], 1.0 op_sel_hi:[1,0]
	v_pk_add_f32 v[144:145], v[144:145], 1.0 op_sel_hi:[1,0]
	v_rcp_f32_e32 v142, v142
	v_rcp_f32_e32 v143, v143
	v_rcp_f32_e32 v144, v144
	v_rcp_f32_e32 v145, v145
	v_pk_mul_f32 v[100:101], v[100:101], v[142:143]
	v_pk_mul_f32 v[102:103], v[102:103], v[144:145]
	v_pk_mul_f32 v[100:101], v[100:101], v[96:97]
	v_pk_mul_f32 v[102:103], v[102:103], v[98:99]
	v_cvt_pk_bf16_f32 v96, v108, v109
	v_cvt_pk_bf16_f32 v97, v110, v111
	v_cvt_pk_bf16_f32 v98, v100, v101
	v_cvt_pk_bf16_f32 v99, v102, v103
	global_store_dwordx4 v130, v[96:99], s[86:87]
	v_add_u32_e32 v130, 0x16000, v130
	v_pk_mul_f32 v[142:143], v[92:93], v[146:147] op_sel_hi:[1,0]
	v_pk_mul_f32 v[144:145], v[94:95], v[146:147] op_sel_hi:[1,0]
	v_exp_f32_e32 v142, v142
	v_exp_f32_e32 v143, v143
	v_exp_f32_e32 v144, v144
	v_exp_f32_e32 v145, v145
	v_pk_add_f32 v[142:143], v[142:143], 1.0 op_sel_hi:[1,0]
	v_pk_add_f32 v[144:145], v[144:145], 1.0 op_sel_hi:[1,0]
	v_rcp_f32_e32 v142, v142
	v_rcp_f32_e32 v143, v143
	v_rcp_f32_e32 v144, v144
	v_rcp_f32_e32 v145, v145
	v_pk_mul_f32 v[92:93], v[92:93], v[142:143]
	v_pk_mul_f32 v[94:95], v[94:95], v[144:145]
	v_pk_mul_f32 v[92:93], v[92:93], v[88:89]
	v_pk_mul_f32 v[94:95], v[94:95], v[90:91]
	v_pk_mul_f32 v[142:143], v[84:85], v[146:147] op_sel_hi:[1,0]
	v_pk_mul_f32 v[144:145], v[86:87], v[146:147] op_sel_hi:[1,0]
	v_exp_f32_e32 v142, v142
	v_exp_f32_e32 v143, v143
	v_exp_f32_e32 v144, v144
	v_exp_f32_e32 v145, v145
	v_pk_add_f32 v[142:143], v[142:143], 1.0 op_sel_hi:[1,0]
	v_pk_add_f32 v[144:145], v[144:145], 1.0 op_sel_hi:[1,0]
	v_rcp_f32_e32 v142, v142
	v_rcp_f32_e32 v143, v143
	v_rcp_f32_e32 v144, v144
	v_rcp_f32_e32 v145, v145
	v_pk_mul_f32 v[84:85], v[84:85], v[142:143]
	v_pk_mul_f32 v[86:87], v[86:87], v[144:145]
	v_pk_mul_f32 v[84:85], v[84:85], v[80:81]
	v_pk_mul_f32 v[86:87], v[86:87], v[82:83]
	v_cvt_pk_bf16_f32 v80, v92, v93
	v_cvt_pk_bf16_f32 v81, v94, v95
	v_cvt_pk_bf16_f32 v82, v84, v85
	v_cvt_pk_bf16_f32 v83, v86, v87
	global_store_dwordx4 v130, v[80:83], s[86:87]
	v_add_u32_e32 v130, 0x16000, v130
	v_pk_mul_f32 v[142:143], v[76:77], v[146:147] op_sel_hi:[1,0]
	v_pk_mul_f32 v[144:145], v[78:79], v[146:147] op_sel_hi:[1,0]
	v_exp_f32_e32 v142, v142
	v_exp_f32_e32 v143, v143
	v_exp_f32_e32 v144, v144
	v_exp_f32_e32 v145, v145
	v_pk_add_f32 v[142:143], v[142:143], 1.0 op_sel_hi:[1,0]
	v_pk_add_f32 v[144:145], v[144:145], 1.0 op_sel_hi:[1,0]
	v_rcp_f32_e32 v142, v142
	v_rcp_f32_e32 v143, v143
	v_rcp_f32_e32 v144, v144
	v_rcp_f32_e32 v145, v145
	v_pk_mul_f32 v[76:77], v[76:77], v[142:143]
	v_pk_mul_f32 v[78:79], v[78:79], v[144:145]
	v_pk_mul_f32 v[76:77], v[76:77], v[72:73]
	v_pk_mul_f32 v[78:79], v[78:79], v[74:75]
	v_pk_mul_f32 v[142:143], v[68:69], v[146:147] op_sel_hi:[1,0]
	v_pk_mul_f32 v[144:145], v[70:71], v[146:147] op_sel_hi:[1,0]
	v_exp_f32_e32 v142, v142
	v_exp_f32_e32 v143, v143
	v_exp_f32_e32 v144, v144
	v_exp_f32_e32 v145, v145
	v_pk_add_f32 v[142:143], v[142:143], 1.0 op_sel_hi:[1,0]
	v_pk_add_f32 v[144:145], v[144:145], 1.0 op_sel_hi:[1,0]
	v_rcp_f32_e32 v142, v142
	v_rcp_f32_e32 v143, v143
	v_rcp_f32_e32 v144, v144
	v_rcp_f32_e32 v145, v145
	v_pk_mul_f32 v[68:69], v[68:69], v[142:143]
	v_pk_mul_f32 v[70:71], v[70:71], v[144:145]
	v_pk_mul_f32 v[68:69], v[68:69], v[64:65]
	v_pk_mul_f32 v[70:71], v[70:71], v[66:67]
	v_cvt_pk_bf16_f32 v64, v76, v77
	v_cvt_pk_bf16_f32 v65, v78, v79
	v_cvt_pk_bf16_f32 v66, v68, v69
	v_cvt_pk_bf16_f32 v67, v70, v71
	global_store_dwordx4 v130, v[64:67], s[86:87]
	v_add_u32_e32 v130, 0x6e000, v130
	v_pk_mul_f32 v[142:143], v[60:61], v[146:147] op_sel_hi:[1,0]
	v_pk_mul_f32 v[144:145], v[62:63], v[146:147] op_sel_hi:[1,0]
	v_exp_f32_e32 v142, v142
	v_exp_f32_e32 v143, v143
	v_exp_f32_e32 v144, v144
	v_exp_f32_e32 v145, v145
	v_pk_add_f32 v[142:143], v[142:143], 1.0 op_sel_hi:[1,0]
	v_pk_add_f32 v[144:145], v[144:145], 1.0 op_sel_hi:[1,0]
	v_rcp_f32_e32 v142, v142
	v_rcp_f32_e32 v143, v143
	v_rcp_f32_e32 v144, v144
	v_rcp_f32_e32 v145, v145
	v_pk_mul_f32 v[60:61], v[60:61], v[142:143]
	v_pk_mul_f32 v[62:63], v[62:63], v[144:145]
	v_pk_mul_f32 v[60:61], v[60:61], v[56:57]
	v_pk_mul_f32 v[62:63], v[62:63], v[58:59]
	v_pk_mul_f32 v[142:143], v[52:53], v[146:147] op_sel_hi:[1,0]
	v_pk_mul_f32 v[144:145], v[54:55], v[146:147] op_sel_hi:[1,0]
	v_exp_f32_e32 v142, v142
	v_exp_f32_e32 v143, v143
	v_exp_f32_e32 v144, v144
	v_exp_f32_e32 v145, v145
	v_pk_add_f32 v[142:143], v[142:143], 1.0 op_sel_hi:[1,0]
	v_pk_add_f32 v[144:145], v[144:145], 1.0 op_sel_hi:[1,0]
	v_rcp_f32_e32 v142, v142
	v_rcp_f32_e32 v143, v143
	v_rcp_f32_e32 v144, v144
	v_rcp_f32_e32 v145, v145
	v_pk_mul_f32 v[52:53], v[52:53], v[142:143]
	v_pk_mul_f32 v[54:55], v[54:55], v[144:145]
	v_pk_mul_f32 v[52:53], v[52:53], v[48:49]
	v_pk_mul_f32 v[54:55], v[54:55], v[50:51]
	v_cvt_pk_bf16_f32 v48, v60, v61
	v_cvt_pk_bf16_f32 v49, v62, v63
	v_cvt_pk_bf16_f32 v50, v52, v53
	v_cvt_pk_bf16_f32 v51, v54, v55
	global_store_dwordx4 v130, v[48:51], s[86:87]
	v_add_u32_e32 v130, 0x16000, v130
	v_pk_mul_f32 v[142:143], v[44:45], v[146:147] op_sel_hi:[1,0]
	v_pk_mul_f32 v[144:145], v[46:47], v[146:147] op_sel_hi:[1,0]
	v_exp_f32_e32 v142, v142
	v_exp_f32_e32 v143, v143
	v_exp_f32_e32 v144, v144
	v_exp_f32_e32 v145, v145
	v_pk_add_f32 v[142:143], v[142:143], 1.0 op_sel_hi:[1,0]
	v_pk_add_f32 v[144:145], v[144:145], 1.0 op_sel_hi:[1,0]
	v_rcp_f32_e32 v142, v142
	v_rcp_f32_e32 v143, v143
	v_rcp_f32_e32 v144, v144
	v_rcp_f32_e32 v145, v145
	v_pk_mul_f32 v[44:45], v[44:45], v[142:143]
	v_pk_mul_f32 v[46:47], v[46:47], v[144:145]
	v_pk_mul_f32 v[44:45], v[44:45], v[40:41]
	v_pk_mul_f32 v[46:47], v[46:47], v[42:43]
	v_pk_mul_f32 v[142:143], v[36:37], v[146:147] op_sel_hi:[1,0]
	v_pk_mul_f32 v[144:145], v[38:39], v[146:147] op_sel_hi:[1,0]
	v_exp_f32_e32 v142, v142
	v_exp_f32_e32 v143, v143
	v_exp_f32_e32 v144, v144
	v_exp_f32_e32 v145, v145
	v_pk_add_f32 v[142:143], v[142:143], 1.0 op_sel_hi:[1,0]
	v_pk_add_f32 v[144:145], v[144:145], 1.0 op_sel_hi:[1,0]
	v_rcp_f32_e32 v142, v142
	v_rcp_f32_e32 v143, v143
	v_rcp_f32_e32 v144, v144
	v_rcp_f32_e32 v145, v145
	v_pk_mul_f32 v[36:37], v[36:37], v[142:143]
	v_pk_mul_f32 v[38:39], v[38:39], v[144:145]
	v_pk_mul_f32 v[36:37], v[36:37], v[32:33]
	v_pk_mul_f32 v[38:39], v[38:39], v[34:35]
	v_cvt_pk_bf16_f32 v32, v44, v45
	v_cvt_pk_bf16_f32 v33, v46, v47
	v_cvt_pk_bf16_f32 v34, v36, v37
	v_cvt_pk_bf16_f32 v35, v38, v39
	global_store_dwordx4 v130, v[32:35], s[86:87]
	v_add_u32_e32 v130, 0x16000, v130
	v_pk_mul_f32 v[142:143], v[28:29], v[146:147] op_sel_hi:[1,0]
	v_pk_mul_f32 v[144:145], v[30:31], v[146:147] op_sel_hi:[1,0]
	v_exp_f32_e32 v142, v142
	v_exp_f32_e32 v143, v143
	v_exp_f32_e32 v144, v144
	v_exp_f32_e32 v145, v145
	v_pk_add_f32 v[142:143], v[142:143], 1.0 op_sel_hi:[1,0]
	v_pk_add_f32 v[144:145], v[144:145], 1.0 op_sel_hi:[1,0]
	v_rcp_f32_e32 v142, v142
	v_rcp_f32_e32 v143, v143
	v_rcp_f32_e32 v144, v144
	v_rcp_f32_e32 v145, v145
	v_pk_mul_f32 v[28:29], v[28:29], v[142:143]
	v_pk_mul_f32 v[30:31], v[30:31], v[144:145]
	v_pk_mul_f32 v[28:29], v[28:29], v[24:25]
	v_pk_mul_f32 v[30:31], v[30:31], v[26:27]
	v_pk_mul_f32 v[142:143], v[20:21], v[146:147] op_sel_hi:[1,0]
	v_pk_mul_f32 v[144:145], v[22:23], v[146:147] op_sel_hi:[1,0]
	v_exp_f32_e32 v142, v142
	v_exp_f32_e32 v143, v143
	v_exp_f32_e32 v144, v144
	v_exp_f32_e32 v145, v145
	v_pk_add_f32 v[142:143], v[142:143], 1.0 op_sel_hi:[1,0]
	v_pk_add_f32 v[144:145], v[144:145], 1.0 op_sel_hi:[1,0]
	v_rcp_f32_e32 v142, v142
	v_rcp_f32_e32 v143, v143
	v_rcp_f32_e32 v144, v144
	v_rcp_f32_e32 v145, v145
	v_pk_mul_f32 v[20:21], v[20:21], v[142:143]
	v_pk_mul_f32 v[22:23], v[22:23], v[144:145]
	v_pk_mul_f32 v[20:21], v[20:21], v[16:17]
	v_pk_mul_f32 v[22:23], v[22:23], v[18:19]
	v_cvt_pk_bf16_f32 v16, v28, v29
	v_cvt_pk_bf16_f32 v17, v30, v31
	v_cvt_pk_bf16_f32 v18, v20, v21
	v_cvt_pk_bf16_f32 v19, v22, v23
	global_store_dwordx4 v130, v[16:19], s[86:87]
	v_add_u32_e32 v130, 0x16000, v130
	v_pk_mul_f32 v[142:143], v[12:13], v[146:147] op_sel_hi:[1,0]
	v_pk_mul_f32 v[144:145], v[14:15], v[146:147] op_sel_hi:[1,0]
	v_exp_f32_e32 v142, v142
	v_exp_f32_e32 v143, v143
	v_exp_f32_e32 v144, v144
	v_exp_f32_e32 v145, v145
	v_pk_add_f32 v[142:143], v[142:143], 1.0 op_sel_hi:[1,0]
	v_pk_add_f32 v[144:145], v[144:145], 1.0 op_sel_hi:[1,0]
	v_rcp_f32_e32 v142, v142
	v_rcp_f32_e32 v143, v143
	v_rcp_f32_e32 v144, v144
	v_rcp_f32_e32 v145, v145
	v_pk_mul_f32 v[12:13], v[12:13], v[142:143]
	v_pk_mul_f32 v[14:15], v[14:15], v[144:145]
	v_pk_mul_f32 v[12:13], v[12:13], v[8:9]
	v_pk_mul_f32 v[14:15], v[14:15], v[10:11]
	v_pk_mul_f32 v[142:143], v[4:5], v[146:147] op_sel_hi:[1,0]
	v_pk_mul_f32 v[144:145], v[6:7], v[146:147] op_sel_hi:[1,0]
	v_exp_f32_e32 v142, v142
	v_exp_f32_e32 v143, v143
	v_exp_f32_e32 v144, v144
	v_exp_f32_e32 v145, v145
	v_pk_add_f32 v[142:143], v[142:143], 1.0 op_sel_hi:[1,0]
	v_pk_add_f32 v[144:145], v[144:145], 1.0 op_sel_hi:[1,0]
	v_rcp_f32_e32 v142, v142
	v_rcp_f32_e32 v143, v143
	v_rcp_f32_e32 v144, v144
	v_rcp_f32_e32 v145, v145
	v_pk_mul_f32 v[4:5], v[4:5], v[142:143]
	v_pk_mul_f32 v[6:7], v[6:7], v[144:145]
	v_pk_mul_f32 v[4:5], v[4:5], v[0:1]
	v_pk_mul_f32 v[6:7], v[6:7], v[2:3]
	v_cvt_pk_bf16_f32 v0, v12, v13
	v_cvt_pk_bf16_f32 v1, v14, v15
	v_cvt_pk_bf16_f32 v2, v4, v5
	v_cvt_pk_bf16_f32 v3, v6, v7
	global_store_dwordx4 v130, v[0:3], s[86:87]
	s_branch .LBB0_133
